# token-0 shadow mixer: 128-step k loop handles 16 k per trip with all loads issued together (was one load round trip per 4 k, 32 in a row); same multiply / fmac order
# speedup vs baseline: 1.0270x; 1.0006x over previous
; DEVI void sk_mixer(const Params& p, int l, const float* __restrict__ SP, float* __restrict__ SM, int b, unsigned char* lds, int wv) {
;     ...
;     const float* w = p.in[13] + (size_t)l * 128 * 640; const float* kn = p.in[12] + (size_t)l * 128;
;     float a = 0.f; for (int k = 0; k < 128; ++k) a += tmp[k] * kn[k] * w[(size_t)k * 640 + h * 128 + 64 + d];
;     M[384 + tid] = a * tmp[128];
;     const float s00 = tmp[136 + h];
;     float mu = 0.f; for (int e = 0; e < 64; ++e) mu += P[2226 + h * 64 + e]; mu *= s00 * (1.f / 64.f);
.LBB0_357:
	v_lshl_add_u64 v[214:215], v[4:5], 0, s[12:13]
	global_load_dwordx4 v[198:201], v33, s[10:11] offset:-8
	global_load_dwordx4 v[202:205], v33, s[10:11] offset:8
	global_load_dwordx4 v[206:209], v33, s[10:11] offset:24
	global_load_dwordx4 v[210:213], v33, s[10:11] offset:40
	global_load_dword v182, v[214:215], off offset:256
	v_add_co_u32_e32 v214, vcc, 0xa00, v214
	v_addc_co_u32_e32 v215, vcc, 0, v215, vcc
	global_load_dword v183, v[214:215], off offset:256
	v_add_co_u32_e32 v214, vcc, 0xa00, v214
	v_addc_co_u32_e32 v215, vcc, 0, v215, vcc
	global_load_dword v184, v[214:215], off offset:256
	v_add_co_u32_e32 v214, vcc, 0xa00, v214
	v_addc_co_u32_e32 v215, vcc, 0, v215, vcc
	global_load_dword v185, v[214:215], off offset:256
	v_add_co_u32_e32 v214, vcc, 0xa00, v214
	v_addc_co_u32_e32 v215, vcc, 0, v215, vcc
	global_load_dword v186, v[214:215], off offset:256
	v_add_co_u32_e32 v214, vcc, 0xa00, v214
	v_addc_co_u32_e32 v215, vcc, 0, v215, vcc
	global_load_dword v187, v[214:215], off offset:256
	v_add_co_u32_e32 v214, vcc, 0xa00, v214
	v_addc_co_u32_e32 v215, vcc, 0, v215, vcc
	global_load_dword v188, v[214:215], off offset:256
	v_add_co_u32_e32 v214, vcc, 0xa00, v214
	v_addc_co_u32_e32 v215, vcc, 0, v215, vcc
	global_load_dword v189, v[214:215], off offset:256
	v_add_co_u32_e32 v214, vcc, 0xa00, v214
	v_addc_co_u32_e32 v215, vcc, 0, v215, vcc
	global_load_dword v190, v[214:215], off offset:256
	v_add_co_u32_e32 v214, vcc, 0xa00, v214
	v_addc_co_u32_e32 v215, vcc, 0, v215, vcc
	global_load_dword v191, v[214:215], off offset:256
	v_add_co_u32_e32 v214, vcc, 0xa00, v214
	v_addc_co_u32_e32 v215, vcc, 0, v215, vcc
	global_load_dword v192, v[214:215], off offset:256
	v_add_co_u32_e32 v214, vcc, 0xa00, v214
	v_addc_co_u32_e32 v215, vcc, 0, v215, vcc
	global_load_dword v193, v[214:215], off offset:256
	v_add_co_u32_e32 v214, vcc, 0xa00, v214
	v_addc_co_u32_e32 v215, vcc, 0, v215, vcc
	global_load_dword v194, v[214:215], off offset:256
	v_add_co_u32_e32 v214, vcc, 0xa00, v214
	v_addc_co_u32_e32 v215, vcc, 0, v215, vcc
	global_load_dword v195, v[214:215], off offset:256
	v_add_co_u32_e32 v214, vcc, 0xa00, v214
	v_addc_co_u32_e32 v215, vcc, 0, v215, vcc
	global_load_dword v196, v[214:215], off offset:256
	v_add_co_u32_e32 v214, vcc, 0xa00, v214
	v_addc_co_u32_e32 v215, vcc, 0, v215, vcc
	global_load_dword v197, v[214:215], off offset:256
	v_mov_b32_e32 v216, s2
	ds_read_b128 v[218:221], v216
	ds_read_b128 v[8:11], v216 offset:16
	s_add_u32 s12, s12, 0xa000
	s_addc_u32 s13, s13, 0
	s_add_i32 s2, s2, 64
	s_add_u32 s10, s10, 64
	s_addc_u32 s11, s11, 0
	s_cmp_eq_u32 s12, 0x50000
	s_waitcnt lgkmcnt(1)
	s_waitcnt vmcnt(15)
	v_mul_f32_e32 v198, v218, v198
	v_mul_f32_e32 v199, v219, v199
	v_fmac_f32_e32 v6, v198, v182
	v_mul_f32_e32 v200, v220, v200
	s_waitcnt vmcnt(14)
	v_fmac_f32_e32 v6, v199, v183
	v_mul_f32_e32 v201, v221, v201
	s_waitcnt vmcnt(13)
	v_fmac_f32_e32 v6, v200, v184
	s_waitcnt vmcnt(12)
	v_fmac_f32_e32 v6, v201, v185
	ds_read_b128 v[218:221], v216 offset:32
	s_waitcnt lgkmcnt(0)
	s_waitcnt vmcnt(11)
	v_mul_f32_e32 v202, v8, v202
	v_mul_f32_e32 v203, v9, v203
	v_fmac_f32_e32 v6, v202, v186
	v_mul_f32_e32 v204, v10, v204
	s_waitcnt vmcnt(10)
	v_fmac_f32_e32 v6, v203, v187
	v_mul_f32_e32 v205, v11, v205
	s_waitcnt vmcnt(9)
	v_fmac_f32_e32 v6, v204, v188
	s_waitcnt vmcnt(8)
	v_fmac_f32_e32 v6, v205, v189
	ds_read_b128 v[8:11], v216 offset:48
	s_waitcnt lgkmcnt(1)
	s_waitcnt vmcnt(7)
	v_mul_f32_e32 v206, v218, v206
	v_mul_f32_e32 v207, v219, v207
	v_fmac_f32_e32 v6, v206, v190
	v_mul_f32_e32 v208, v220, v208
	s_waitcnt vmcnt(6)
	v_fmac_f32_e32 v6, v207, v191
	v_mul_f32_e32 v209, v221, v209
	s_waitcnt vmcnt(5)
	v_fmac_f32_e32 v6, v208, v192
	s_waitcnt vmcnt(4)
	v_fmac_f32_e32 v6, v209, v193
	s_waitcnt lgkmcnt(0)
	s_waitcnt vmcnt(3)
	v_mul_f32_e32 v210, v8, v210
	v_mul_f32_e32 v211, v9, v211
	v_fmac_f32_e32 v6, v210, v194
	v_mul_f32_e32 v212, v10, v212
	s_waitcnt vmcnt(2)
	v_fmac_f32_e32 v6, v211, v195
	v_mul_f32_e32 v213, v11, v213
	s_waitcnt vmcnt(1)
	v_fmac_f32_e32 v6, v212, v196
	s_waitcnt vmcnt(0)
	v_fmac_f32_e32 v6, v213, v197
	s_cbranch_scc0 .LBB0_357
	ds_read_b32 v7, v33 offset:512
	v_lshl_add_u32 v1, v1, 2, 0
	ds_read_b32 v1, v1 offset:544
	v_lshl_add_u64 v[4:5], v[2:3], 2, s[8:9]
	v_and_b32_e32 v2, 0xffffffc0, v2
	s_waitcnt lgkmcnt(1)
	v_mul_f32_e32 v3, v6, v7
	global_store_dword v[4:5], v3, off offset:1536
	v_add_u32_e32 v3, 0x8b2, v2
	v_mov_b32_e32 v6, 0
	s_mov_b32 s2, 0

; DEVI void sk_mixer(const Params& p, int l, const float* __restrict__ SP, float* __restrict__ SM, int b, unsigned char* lds, int wv) {
;     ...
;     const float* w = p.in[13] + (size_t)l * 128 * 640; const float* kn = p.in[12] + (size_t)l * 128;
;     float a = 0.f; for (int k = 0; k < 128; ++k) a += tmp[k] * kn[k] * w[(size_t)k * 640 + h * 128 + 64 + d];
;     M[384 + tid] = a * tmp[128];
;     const float s00 = tmp[136 + h];
;     float mu = 0.f; for (int e = 0; e < 64; ++e) mu += P[2226 + h * 64 + e]; mu *= s00 * (1.f / 64.f);
.LBB0_731:
	v_lshl_add_u64 v[214:215], v[4:5], 0, s[12:13]
	global_load_dwordx4 v[198:201], v33, s[10:11] offset:-8
	global_load_dwordx4 v[202:205], v33, s[10:11] offset:8
	global_load_dwordx4 v[206:209], v33, s[10:11] offset:24
	global_load_dwordx4 v[210:213], v33, s[10:11] offset:40
	global_load_dword v182, v[214:215], off offset:256
	v_add_co_u32_e32 v214, vcc, 0xa00, v214
	v_addc_co_u32_e32 v215, vcc, 0, v215, vcc
	global_load_dword v183, v[214:215], off offset:256
	v_add_co_u32_e32 v214, vcc, 0xa00, v214
	v_addc_co_u32_e32 v215, vcc, 0, v215, vcc
	global_load_dword v184, v[214:215], off offset:256
	v_add_co_u32_e32 v214, vcc, 0xa00, v214
	v_addc_co_u32_e32 v215, vcc, 0, v215, vcc
	global_load_dword v185, v[214:215], off offset:256
	v_add_co_u32_e32 v214, vcc, 0xa00, v214
	v_addc_co_u32_e32 v215, vcc, 0, v215, vcc
	global_load_dword v186, v[214:215], off offset:256
	v_add_co_u32_e32 v214, vcc, 0xa00, v214
	v_addc_co_u32_e32 v215, vcc, 0, v215, vcc
	global_load_dword v187, v[214:215], off offset:256
	v_add_co_u32_e32 v214, vcc, 0xa00, v214
	v_addc_co_u32_e32 v215, vcc, 0, v215, vcc
	global_load_dword v188, v[214:215], off offset:256
	v_add_co_u32_e32 v214, vcc, 0xa00, v214
	v_addc_co_u32_e32 v215, vcc, 0, v215, vcc
	global_load_dword v189, v[214:215], off offset:256
	v_add_co_u32_e32 v214, vcc, 0xa00, v214
	v_addc_co_u32_e32 v215, vcc, 0, v215, vcc
	global_load_dword v190, v[214:215], off offset:256
	v_add_co_u32_e32 v214, vcc, 0xa00, v214
	v_addc_co_u32_e32 v215, vcc, 0, v215, vcc
	global_load_dword v191, v[214:215], off offset:256
	v_add_co_u32_e32 v214, vcc, 0xa00, v214
	v_addc_co_u32_e32 v215, vcc, 0, v215, vcc
	global_load_dword v192, v[214:215], off offset:256
	v_add_co_u32_e32 v214, vcc, 0xa00, v214
	v_addc_co_u32_e32 v215, vcc, 0, v215, vcc
	global_load_dword v193, v[214:215], off offset:256
	v_add_co_u32_e32 v214, vcc, 0xa00, v214
	v_addc_co_u32_e32 v215, vcc, 0, v215, vcc
	global_load_dword v194, v[214:215], off offset:256
	v_add_co_u32_e32 v214, vcc, 0xa00, v214
	v_addc_co_u32_e32 v215, vcc, 0, v215, vcc
	global_load_dword v195, v[214:215], off offset:256
	v_add_co_u32_e32 v214, vcc, 0xa00, v214
	v_addc_co_u32_e32 v215, vcc, 0, v215, vcc
	global_load_dword v196, v[214:215], off offset:256
	v_add_co_u32_e32 v214, vcc, 0xa00, v214
	v_addc_co_u32_e32 v215, vcc, 0, v215, vcc
	global_load_dword v197, v[214:215], off offset:256
	v_mov_b32_e32 v216, s2
	ds_read_b128 v[218:221], v216
	ds_read_b128 v[8:11], v216 offset:16
	s_add_u32 s12, s12, 0xa000
	s_addc_u32 s13, s13, 0
	s_add_i32 s2, s2, 64
	s_add_u32 s10, s10, 64
	s_addc_u32 s11, s11, 0
	s_cmp_eq_u32 s12, 0x50000
	s_waitcnt lgkmcnt(1)
	s_waitcnt vmcnt(15)
	v_mul_f32_e32 v198, v218, v198
	v_mul_f32_e32 v199, v219, v199
	v_fmac_f32_e32 v6, v198, v182
	v_mul_f32_e32 v200, v220, v200
	s_waitcnt vmcnt(14)
	v_fmac_f32_e32 v6, v199, v183
	v_mul_f32_e32 v201, v221, v201
	s_waitcnt vmcnt(13)
	v_fmac_f32_e32 v6, v200, v184
	s_waitcnt vmcnt(12)
	v_fmac_f32_e32 v6, v201, v185
	ds_read_b128 v[218:221], v216 offset:32
	s_waitcnt lgkmcnt(0)
	s_waitcnt vmcnt(11)
	v_mul_f32_e32 v202, v8, v202
	v_mul_f32_e32 v203, v9, v203
	v_fmac_f32_e32 v6, v202, v186
	v_mul_f32_e32 v204, v10, v204
	s_waitcnt vmcnt(10)
	v_fmac_f32_e32 v6, v203, v187
	v_mul_f32_e32 v205, v11, v205
	s_waitcnt vmcnt(9)
	v_fmac_f32_e32 v6, v204, v188
	s_waitcnt vmcnt(8)
	v_fmac_f32_e32 v6, v205, v189
	ds_read_b128 v[8:11], v216 offset:48
	s_waitcnt lgkmcnt(1)
	s_waitcnt vmcnt(7)
	v_mul_f32_e32 v206, v218, v206
	v_mul_f32_e32 v207, v219, v207
	v_fmac_f32_e32 v6, v206, v190
	v_mul_f32_e32 v208, v220, v208
	s_waitcnt vmcnt(6)
	v_fmac_f32_e32 v6, v207, v191
	v_mul_f32_e32 v209, v221, v209
	s_waitcnt vmcnt(5)
	v_fmac_f32_e32 v6, v208, v192
	s_waitcnt vmcnt(4)
	v_fmac_f32_e32 v6, v209, v193
	s_waitcnt lgkmcnt(0)
	s_waitcnt vmcnt(3)
	v_mul_f32_e32 v210, v8, v210
	v_mul_f32_e32 v211, v9, v211
	v_fmac_f32_e32 v6, v210, v194
	v_mul_f32_e32 v212, v10, v212
	s_waitcnt vmcnt(2)
	v_fmac_f32_e32 v6, v211, v195
	v_mul_f32_e32 v213, v11, v213
	s_waitcnt vmcnt(1)
	v_fmac_f32_e32 v6, v212, v196
	s_waitcnt vmcnt(0)
	v_fmac_f32_e32 v6, v213, v197
	s_cbranch_scc0 .LBB0_731
	ds_read_b32 v4, v33 offset:512
	v_lshl_add_u32 v1, v1, 2, 0
	ds_read_b32 v1, v1 offset:544
	s_mov_b32 s2, 0
	s_waitcnt lgkmcnt(1)
	v_mul_f32_e32 v6, v6, v4
	v_lshl_add_u64 v[4:5], v[2:3], 2, s[8:9]
	v_and_b32_e32 v2, 0xffffffc0, v2
	global_store_dword v[4:5], v6, off offset:1536
	v_add_u32_e32 v3, 0x8b2, v2
	v_mov_b32_e32 v6, 0

; DEVI void sk_mixer(const Params& p, int l, const float* __restrict__ SP, float* __restrict__ SM, int b, unsigned char* lds, int wv) {
;     ...
;     const float* w = p.in[13] + (size_t)l * 128 * 640; const float* kn = p.in[12] + (size_t)l * 128;
;     float a = 0.f; for (int k = 0; k < 128; ++k) a += tmp[k] * kn[k] * w[(size_t)k * 640 + h * 128 + 64 + d];
;     M[384 + tid] = a * tmp[128];
;     const float s00 = tmp[136 + h];
;     float mu = 0.f; for (int e = 0; e < 64; ++e) mu += P[2226 + h * 64 + e]; mu *= s00 * (1.f / 64.f);
.LBB0_1149:
	v_lshl_add_u64 v[214:215], v[4:5], 0, s[16:17]
	global_load_dwordx4 v[198:201], v33, s[14:15] offset:-8
	global_load_dwordx4 v[202:205], v33, s[14:15] offset:8
	global_load_dwordx4 v[206:209], v33, s[14:15] offset:24
	global_load_dwordx4 v[210:213], v33, s[14:15] offset:40
	global_load_dword v182, v[214:215], off offset:256
	v_add_co_u32_e32 v214, vcc, 0xa00, v214
	v_addc_co_u32_e32 v215, vcc, 0, v215, vcc
	global_load_dword v183, v[214:215], off offset:256
	v_add_co_u32_e32 v214, vcc, 0xa00, v214
	v_addc_co_u32_e32 v215, vcc, 0, v215, vcc
	global_load_dword v184, v[214:215], off offset:256
	v_add_co_u32_e32 v214, vcc, 0xa00, v214
	v_addc_co_u32_e32 v215, vcc, 0, v215, vcc
	global_load_dword v185, v[214:215], off offset:256
	v_add_co_u32_e32 v214, vcc, 0xa00, v214
	v_addc_co_u32_e32 v215, vcc, 0, v215, vcc
	global_load_dword v186, v[214:215], off offset:256
	v_add_co_u32_e32 v214, vcc, 0xa00, v214
	v_addc_co_u32_e32 v215, vcc, 0, v215, vcc
	global_load_dword v187, v[214:215], off offset:256
	v_add_co_u32_e32 v214, vcc, 0xa00, v214
	v_addc_co_u32_e32 v215, vcc, 0, v215, vcc
	global_load_dword v188, v[214:215], off offset:256
	v_add_co_u32_e32 v214, vcc, 0xa00, v214
	v_addc_co_u32_e32 v215, vcc, 0, v215, vcc
	global_load_dword v189, v[214:215], off offset:256
	v_add_co_u32_e32 v214, vcc, 0xa00, v214
	v_addc_co_u32_e32 v215, vcc, 0, v215, vcc
	global_load_dword v190, v[214:215], off offset:256
	v_add_co_u32_e32 v214, vcc, 0xa00, v214
	v_addc_co_u32_e32 v215, vcc, 0, v215, vcc
	global_load_dword v191, v[214:215], off offset:256
	v_add_co_u32_e32 v214, vcc, 0xa00, v214
	v_addc_co_u32_e32 v215, vcc, 0, v215, vcc
	global_load_dword v192, v[214:215], off offset:256
	v_add_co_u32_e32 v214, vcc, 0xa00, v214
	v_addc_co_u32_e32 v215, vcc, 0, v215, vcc
	global_load_dword v193, v[214:215], off offset:256
	v_add_co_u32_e32 v214, vcc, 0xa00, v214
	v_addc_co_u32_e32 v215, vcc, 0, v215, vcc
	global_load_dword v194, v[214:215], off offset:256
	v_add_co_u32_e32 v214, vcc, 0xa00, v214
	v_addc_co_u32_e32 v215, vcc, 0, v215, vcc
	global_load_dword v195, v[214:215], off offset:256
	v_add_co_u32_e32 v214, vcc, 0xa00, v214
	v_addc_co_u32_e32 v215, vcc, 0, v215, vcc
	global_load_dword v196, v[214:215], off offset:256
	v_add_co_u32_e32 v214, vcc, 0xa00, v214
	v_addc_co_u32_e32 v215, vcc, 0, v215, vcc
	global_load_dword v197, v[214:215], off offset:256
	v_mov_b32_e32 v216, s2
	ds_read_b128 v[218:221], v216
	ds_read_b128 v[8:11], v216 offset:16
	s_add_u32 s16, s16, 0xa000
	s_addc_u32 s17, s17, 0
	s_add_i32 s2, s2, 64
	s_add_u32 s14, s14, 64
	s_addc_u32 s15, s15, 0
	s_cmp_eq_u32 s16, 0x50000
	s_waitcnt lgkmcnt(1)
	s_waitcnt vmcnt(15)
	v_mul_f32_e32 v198, v218, v198
	v_mul_f32_e32 v199, v219, v199
	v_fmac_f32_e32 v6, v198, v182
	v_mul_f32_e32 v200, v220, v200
	s_waitcnt vmcnt(14)
	v_fmac_f32_e32 v6, v199, v183
	v_mul_f32_e32 v201, v221, v201
	s_waitcnt vmcnt(13)
	v_fmac_f32_e32 v6, v200, v184
	s_waitcnt vmcnt(12)
	v_fmac_f32_e32 v6, v201, v185
	ds_read_b128 v[218:221], v216 offset:32
	s_waitcnt lgkmcnt(0)
	s_waitcnt vmcnt(11)
	v_mul_f32_e32 v202, v8, v202
	v_mul_f32_e32 v203, v9, v203
	v_fmac_f32_e32 v6, v202, v186
	v_mul_f32_e32 v204, v10, v204
	s_waitcnt vmcnt(10)
	v_fmac_f32_e32 v6, v203, v187
	v_mul_f32_e32 v205, v11, v205
	s_waitcnt vmcnt(9)
	v_fmac_f32_e32 v6, v204, v188
	s_waitcnt vmcnt(8)
	v_fmac_f32_e32 v6, v205, v189
	ds_read_b128 v[8:11], v216 offset:48
	s_waitcnt lgkmcnt(1)
	s_waitcnt vmcnt(7)
	v_mul_f32_e32 v206, v218, v206
	v_mul_f32_e32 v207, v219, v207
	v_fmac_f32_e32 v6, v206, v190
	v_mul_f32_e32 v208, v220, v208
	s_waitcnt vmcnt(6)
	v_fmac_f32_e32 v6, v207, v191
	v_mul_f32_e32 v209, v221, v209
	s_waitcnt vmcnt(5)
	v_fmac_f32_e32 v6, v208, v192
	s_waitcnt vmcnt(4)
	v_fmac_f32_e32 v6, v209, v193
	s_waitcnt lgkmcnt(0)
	s_waitcnt vmcnt(3)
	v_mul_f32_e32 v210, v8, v210
	v_mul_f32_e32 v211, v9, v211
	v_fmac_f32_e32 v6, v210, v194
	v_mul_f32_e32 v212, v10, v212
	s_waitcnt vmcnt(2)
	v_fmac_f32_e32 v6, v211, v195
	v_mul_f32_e32 v213, v11, v213
	s_waitcnt vmcnt(1)
	v_fmac_f32_e32 v6, v212, v196
	s_waitcnt vmcnt(0)
	v_fmac_f32_e32 v6, v213, v197
	s_cbranch_scc0 .LBB0_1149
	ds_read_b32 v4, v33 offset:512
	v_lshl_add_u32 v1, v1, 2, 0
	ds_read_b32 v1, v1 offset:544
	s_mov_b32 s2, 0
	s_waitcnt lgkmcnt(1)
	v_mul_f32_e32 v6, v6, v4
	v_lshl_add_u64 v[4:5], v[2:3], 2, s[6:7]
	v_and_b32_e32 v2, 0xffffffc0, v2
	global_store_dword v[4:5], v6, off offset:1536
	v_add_u32_e32 v3, 0x8b2, v2
	v_mov_b32_e32 v6, 0

; DEVI void sk_mixer(const Params& p, int l, const float* __restrict__ SP, float* __restrict__ SM, int b, unsigned char* lds, int wv) {
;     ...
;     const float* w = p.in[13] + (size_t)l * 128 * 640; const float* kn = p.in[12] + (size_t)l * 128;
;     float a = 0.f; for (int k = 0; k < 128; ++k) a += tmp[k] * kn[k] * w[(size_t)k * 640 + h * 128 + 64 + d];
;     M[384 + tid] = a * tmp[128];
;     const float s00 = tmp[136 + h];
;     float mu = 0.f; for (int e = 0; e < 64; ++e) mu += P[2226 + h * 64 + e]; mu *= s00 * (1.f / 64.f);
.LBB0_1906:
	v_lshl_add_u64 v[214:215], v[4:5], 0, s[18:19]
	global_load_dwordx4 v[198:201], v33, s[16:17] offset:-8
	global_load_dwordx4 v[202:205], v33, s[16:17] offset:8
	global_load_dwordx4 v[206:209], v33, s[16:17] offset:24
	global_load_dwordx4 v[210:213], v33, s[16:17] offset:40
	global_load_dword v182, v[214:215], off offset:256
	v_add_co_u32_e32 v214, vcc, 0xa00, v214
	v_addc_co_u32_e32 v215, vcc, 0, v215, vcc
	global_load_dword v183, v[214:215], off offset:256
	v_add_co_u32_e32 v214, vcc, 0xa00, v214
	v_addc_co_u32_e32 v215, vcc, 0, v215, vcc
	global_load_dword v184, v[214:215], off offset:256
	v_add_co_u32_e32 v214, vcc, 0xa00, v214
	v_addc_co_u32_e32 v215, vcc, 0, v215, vcc
	global_load_dword v185, v[214:215], off offset:256
	v_add_co_u32_e32 v214, vcc, 0xa00, v214
	v_addc_co_u32_e32 v215, vcc, 0, v215, vcc
	global_load_dword v186, v[214:215], off offset:256
	v_add_co_u32_e32 v214, vcc, 0xa00, v214
	v_addc_co_u32_e32 v215, vcc, 0, v215, vcc
	global_load_dword v187, v[214:215], off offset:256
	v_add_co_u32_e32 v214, vcc, 0xa00, v214
	v_addc_co_u32_e32 v215, vcc, 0, v215, vcc
	global_load_dword v188, v[214:215], off offset:256
	v_add_co_u32_e32 v214, vcc, 0xa00, v214
	v_addc_co_u32_e32 v215, vcc, 0, v215, vcc
	global_load_dword v189, v[214:215], off offset:256
	v_add_co_u32_e32 v214, vcc, 0xa00, v214
	v_addc_co_u32_e32 v215, vcc, 0, v215, vcc
	global_load_dword v190, v[214:215], off offset:256
	v_add_co_u32_e32 v214, vcc, 0xa00, v214
	v_addc_co_u32_e32 v215, vcc, 0, v215, vcc
	global_load_dword v191, v[214:215], off offset:256
	v_add_co_u32_e32 v214, vcc, 0xa00, v214
	v_addc_co_u32_e32 v215, vcc, 0, v215, vcc
	global_load_dword v192, v[214:215], off offset:256
	v_add_co_u32_e32 v214, vcc, 0xa00, v214
	v_addc_co_u32_e32 v215, vcc, 0, v215, vcc
	global_load_dword v193, v[214:215], off offset:256
	v_add_co_u32_e32 v214, vcc, 0xa00, v214
	v_addc_co_u32_e32 v215, vcc, 0, v215, vcc
	global_load_dword v194, v[214:215], off offset:256
	v_add_co_u32_e32 v214, vcc, 0xa00, v214
	v_addc_co_u32_e32 v215, vcc, 0, v215, vcc
	global_load_dword v195, v[214:215], off offset:256
	v_add_co_u32_e32 v214, vcc, 0xa00, v214
	v_addc_co_u32_e32 v215, vcc, 0, v215, vcc
	global_load_dword v196, v[214:215], off offset:256
	v_add_co_u32_e32 v214, vcc, 0xa00, v214
	v_addc_co_u32_e32 v215, vcc, 0, v215, vcc
	global_load_dword v197, v[214:215], off offset:256
	v_mov_b32_e32 v216, s2
	ds_read_b128 v[218:221], v216
	ds_read_b128 v[8:11], v216 offset:16
	s_add_u32 s18, s18, 0xa000
	s_addc_u32 s19, s19, 0
	s_add_i32 s2, s2, 64
	s_add_u32 s16, s16, 64
	s_addc_u32 s17, s17, 0
	s_cmp_eq_u32 s18, 0x50000
	s_waitcnt lgkmcnt(1)
	s_waitcnt vmcnt(15)
	v_mul_f32_e32 v198, v218, v198
	v_mul_f32_e32 v199, v219, v199
	v_fmac_f32_e32 v6, v198, v182
	v_mul_f32_e32 v200, v220, v200
	s_waitcnt vmcnt(14)
	v_fmac_f32_e32 v6, v199, v183
	v_mul_f32_e32 v201, v221, v201
	s_waitcnt vmcnt(13)
	v_fmac_f32_e32 v6, v200, v184
	s_waitcnt vmcnt(12)
	v_fmac_f32_e32 v6, v201, v185
	ds_read_b128 v[218:221], v216 offset:32
	s_waitcnt lgkmcnt(0)
	s_waitcnt vmcnt(11)
	v_mul_f32_e32 v202, v8, v202
	v_mul_f32_e32 v203, v9, v203
	v_fmac_f32_e32 v6, v202, v186
	v_mul_f32_e32 v204, v10, v204
	s_waitcnt vmcnt(10)
	v_fmac_f32_e32 v6, v203, v187
	v_mul_f32_e32 v205, v11, v205
	s_waitcnt vmcnt(9)
	v_fmac_f32_e32 v6, v204, v188
	s_waitcnt vmcnt(8)
	v_fmac_f32_e32 v6, v205, v189
	ds_read_b128 v[8:11], v216 offset:48
	s_waitcnt lgkmcnt(1)
	s_waitcnt vmcnt(7)
	v_mul_f32_e32 v206, v218, v206
	v_mul_f32_e32 v207, v219, v207
	v_fmac_f32_e32 v6, v206, v190
	v_mul_f32_e32 v208, v220, v208
	s_waitcnt vmcnt(6)
	v_fmac_f32_e32 v6, v207, v191
	v_mul_f32_e32 v209, v221, v209
	s_waitcnt vmcnt(5)
	v_fmac_f32_e32 v6, v208, v192
	s_waitcnt vmcnt(4)
	v_fmac_f32_e32 v6, v209, v193
	s_waitcnt lgkmcnt(0)
	s_waitcnt vmcnt(3)
	v_mul_f32_e32 v210, v8, v210
	v_mul_f32_e32 v211, v9, v211
	v_fmac_f32_e32 v6, v210, v194
	v_mul_f32_e32 v212, v10, v212
	s_waitcnt vmcnt(2)
	v_fmac_f32_e32 v6, v211, v195
	v_mul_f32_e32 v213, v11, v213
	s_waitcnt vmcnt(1)
	v_fmac_f32_e32 v6, v212, v196
	s_waitcnt vmcnt(0)
	v_fmac_f32_e32 v6, v213, v197
	s_cbranch_scc0 .LBB0_1906
	ds_read_b32 v4, v33 offset:512
	v_lshl_add_u32 v1, v1, 2, 0
	ds_read_b32 v1, v1 offset:544
	s_mov_b32 s2, 0
	s_waitcnt lgkmcnt(1)
	v_mul_f32_e32 v6, v6, v4
	v_lshl_add_u64 v[4:5], v[2:3], 2, s[8:9]
	v_and_b32_e32 v2, 0xffffffc0, v2
	global_store_dword v[4:5], v6, off offset:1536
	v_add_u32_e32 v3, 0x8b2, v2
	v_mov_b32_e32 v6, 0
